# ret_state chunk loop: running-state stores issued after the trip's K/V loads (they no longer sit in front of the next trip's counted wait)
# baseline (speedup 1.0000x reference)
; DEVI void ph_ret_state(const int wv, const Params& p, int l, unsigned char* lds_raw) {
;     ...
;     for (int it = blockIdx.x; it < 256; it += gridDim.x) {
;         const int b = it >> 4, h = (it >> 2) & 3, dir = (it >> 1) & 1, half = it & 1;
;         const float e_ = p.in[9][(l * 2 + dir) * 4 + h];
;         const float lg2 = log1pf(-exp2f(-e_)) * 1.4426950408889634f;
;         const float gC = exp2f(128.0f * lg2);
;         f32x4 R[2]; R[0] = (f32x4){0.f, 0.f, 0.f, 0.f}; R[1] = R[0];
;         const int j0 = tid >> 3, g80 = tid & 7;
;         const float wj0 = exp2f((float)(dir == 0 ? 127 - j0 : j0) * lg2), wj1 = exp2f((float)(dir == 0 ? 63 - j0 : j0 + 64) * lg2);
;         u32x4 kwr[2], vwr[2];
;     ...
;         RS_LOAD(0);
;         __syncthreads();
;         RS_WRITE(0);
;         RS_LOAD(1);
.LBB0_542:
	s_bfe_u32 s2, s29, 0x10001
	s_lshl_b32 s0, s2, 2
	s_bfe_u32 s3, s29, 0x20002
	s_or_b32 s0, s0, s28
	s_or_b32 s18, s0, s3
	s_ashr_i32 s37, s29, 4
	s_lshl_b64 s[0:1], s[18:19], 2
	s_add_u32 s0, s78, s0
	s_addc_u32 s1, s79, s1
	global_load_dword v2, v1, s[0:1]
	s_mov_b32 s0, 0x42fc0000
	v_mov_b64_e32 v[14:15], s[24:25]
	s_mov_b32 s5, s19
	s_mov_b32 s7, s19
	v_lshlrev_b32_e32 v0, 1, v18
	v_lshl_add_u32 v57, s37, 11, v46
	v_add_u32_e32 v88, v50, v49
	s_waitcnt vmcnt(0)
	v_cmp_lt_f32_e32 vcc, s0, v2
	s_nop 1
	v_cndmask_b32_e32 v3, 0, v234, vcc
	v_sub_f32_e32 v2, v3, v2
	s_and_b64 s[0:1], vcc, exec
	v_exp_f32_e32 v2, v2
	s_cselect_b32 s0, 0xffffffc0, 0
	s_lshl_b32 s1, s37, 8
	s_lshl_b32 s8, s2, 7
	s_or_b32 s1, s1, s8
	s_add_i32 s1, s1, 0x8000
	v_add_u32_e32 v4, s1, v25
	s_lshl_b32 s6, s29, 6
	s_waitcnt lgkmcnt(0)
	v_ldexp_f32 v24, v2, s0
	v_add_u32_e32 v6, 64, v4
	s_lshl_b32 s4, s3, 7
	s_lshl_b32 s18, s3, 8
	s_and_b32 s36, s6, 64
	s_xor_b32 s9, s1, 0x80
	v_mad_i64_i32 v[2:3], s[0:1], v4, s46, v[14:15]
	v_sub_f32_e32 v26, 1.0, v24
	v_mad_i64_i32 v[16:17], s[0:1], v6, s46, v[14:15]
	s_lshl_b32 s6, s36, 1
	v_lshl_add_u64 v[4:5], v[2:3], 0, s[4:5]
	v_lshl_add_u64 v[2:3], v[2:3], 0, s[18:19]
	v_add_f32_e32 v10, -1.0, v26
	v_frexp_mant_f32_e32 v11, v26
	v_cvt_f64_f32_e32 v[6:7], v26
	s_mov_b32 s0, 0x3f2aaaab
	v_lshl_add_u64 v[2:3], v[2:3], 0, s[6:7]
	v_lshl_add_u64 v[8:9], v[16:17], 0, s[4:5]
	v_sub_f32_e32 v12, v10, v26
	v_frexp_exp_i32_f64_e32 v6, v[6:7]
	v_cmp_gt_f32_e32 vcc, s0, v11
	v_lshl_add_u64 v[4:5], v[4:5], 0, v[0:1]
	v_sub_f32_e64 v27, -v24, v10
	v_lshl_add_u64 v[2:3], v[2:3], 0, v[0:1]
	v_lshl_add_u64 v[22:23], v[8:9], 0, v[0:1]
	v_add_f32_e32 v28, 1.0, v12
	v_subbrev_co_u32_e32 v29, vcc, 0, v6, vcc
	global_load_dwordx4 v[10:13], v[4:5], off
	global_load_dwordx4 v[6:9], v[2:3], off offset:512
	s_nop 0
	global_load_dwordx4 v[2:5], v[22:23], off
	v_add_f32_e32 v23, v27, v28
	v_sub_u32_e32 v27, 0, v29
	v_ldexp_f32 v26, v26, v27
	v_cvt_f32_i32_e32 v22, v29
	v_add_f32_e32 v28, -1.0, v26
	v_add_f32_e32 v29, 1.0, v26
	v_ldexp_f32 v23, v23, v27
	v_add_f32_e32 v27, 1.0, v28
	v_add_f32_e32 v30, -1.0, v29
	v_sub_f32_e32 v27, v26, v27
	v_sub_f32_e32 v26, v26, v30
	v_add_f32_e32 v30, v23, v27
	v_add_f32_e32 v23, v23, v26
	v_add_f32_e32 v32, v29, v23
	v_rcp_f32_e32 v33, v32
	v_add_f32_e32 v27, v28, v30
	v_sub_f32_e32 v28, v27, v28
	v_sub_f32_e32 v26, v32, v29
	v_mul_f32_e32 v35, v27, v33
	v_sub_f32_e32 v34, v30, v28
	v_mul_f32_e32 v28, v32, v35
	v_sub_f32_e32 v23, v23, v26
	v_fma_f32 v30, v35, v32, -v28
	v_fmac_f32_e32 v30, v35, v23
	v_add_f32_e32 v26, v28, v30
	v_sub_f32_e32 v29, v27, v26
	v_mov_b32_e32 v31, v26
	v_pk_add_f32 v[26:27], v[26:27], v[28:29] neg_lo:[0,1] neg_hi:[0,1]
	s_mov_b32 s0, 0x3f317218
	v_pk_add_f32 v[26:27], v[26:27], v[30:31] neg_lo:[0,1] neg_hi:[0,1]
	v_cmp_nlt_f32_e32 vcc, 1.0, v24
	v_add_f32_e32 v27, v34, v27
	v_add_f32_e32 v26, v26, v27
	v_add_f32_e32 v27, v29, v26
	v_mul_f32_e32 v31, v33, v27
	v_mul_f32_e32 v28, v32, v31
	v_sub_f32_e32 v29, v29, v27
	v_add_f32_e32 v36, v35, v31
	v_fma_f32 v30, v31, v32, -v28
	v_add_f32_e32 v34, v26, v29
	v_sub_f32_e32 v26, v36, v35
	v_fmac_f32_e32 v30, v31, v23
	v_sub_f32_e32 v23, v31, v26
	v_add_f32_e32 v26, v28, v30
	v_sub_f32_e32 v29, v27, v26
	v_mov_b32_e32 v31, v26
	v_pk_add_f32 v[26:27], v[26:27], v[28:29] neg_lo:[0,1] neg_hi:[0,1]
	s_lshl_b32 s31, s3, 6
	v_pk_add_f32 v[26:27], v[26:27], v[30:31] neg_lo:[0,1] neg_hi:[0,1]
	v_lshl_add_u64 v[16:17], v[16:17], 0, s[18:19]
	v_add_f32_e32 v27, v34, v27
	v_add_f32_e32 v26, v26, v27
	v_add_f32_e32 v26, v29, v26
	v_mul_f32_e32 v26, v33, v26
	v_add_f32_e32 v23, v23, v26
	v_add_f32_e32 v26, v36, v23
	v_mul_f32_e32 v28, v26, v26
	v_sub_f32_e32 v29, v26, v36
	v_fmamk_f32 v30, v28, 0x3e9b6dac, v224
	v_sub_f32_e32 v29, v23, v29
	v_mul_f32_e32 v23, v26, v28
	v_fmaak_f32 v199, v28, v30, 0x3f2aaada
	v_ldexp_f32 v31, v29, 1
	v_pk_mul_f32 v[28:29], v[22:23], v[198:199]
	v_ldexp_f32 v27, v26, 1
	v_fma_f32 v26, v22, s0, -v28
	v_fmac_f32_e32 v26, 0xb102e308, v22
	v_pk_add_f32 v[22:23], v[28:29], v[26:27]
	v_mov_b32_e32 v30, v28
	v_sub_f32_e32 v34, v23, v27
	v_pk_add_f32 v[32:33], v[22:23], v[28:29] neg_lo:[0,1] neg_hi:[0,1]
	v_sub_f32_e32 v29, v29, v34
	v_add_f32_e32 v31, v31, v29
	v_pk_add_f32 v[36:37], v[22:23], v[30:31]
	v_mov_b32_e32 v27, v22
	v_mov_b32_e32 v33, v37
	v_pk_add_f32 v[38:39], v[26:27], v[32:33] neg_lo:[0,1] neg_hi:[0,1]
	v_pk_add_f32 v[26:27], v[26:27], v[32:33]
	v_mov_b32_e32 v28, v23
	v_mov_b32_e32 v35, v22
	v_pk_add_f32 v[22:23], v[26:27], v[22:23] op_sel:[1,0] op_sel_hi:[0,1] neg_lo:[0,1] neg_hi:[0,1]
	v_mov_b32_e32 v34, v31
	v_mov_b32_e32 v30, v37
	v_mov_b32_e32 v31, v27
	v_mov_b32_e32 v29, v22
	v_pk_add_f32 v[32:33], v[36:37], v[22:23] op_sel_hi:[1,0] neg_lo:[0,1] neg_hi:[0,1]
	v_pk_add_f32 v[22:23], v[30:31], v[28:29] neg_lo:[0,1] neg_hi:[0,1]
	v_mov_b32_e32 v32, v38
	v_pk_add_f32 v[22:23], v[34:35], v[22:23] neg_lo:[0,1] neg_hi:[0,1]
	v_mov_b32_e32 v39, v27
	v_pk_add_f32 v[28:29], v[32:33], v[22:23]
	s_mov_b32 s0, 0x33800000
	v_pk_add_f32 v[30:31], v[28:29], v[28:29] op_sel:[0,1] op_sel_hi:[1,0]
	v_cmp_lt_f32_e64 s[0:1], |v24|, s0
	v_pk_add_f32 v[26:27], v[26:27], v[30:31] op_sel:[1,0] op_sel_hi:[0,1]
	v_mov_b32_e32 v29, v26
	v_mov_b32_e32 v23, v30
	v_pk_add_f32 v[30:31], v[28:29], v[38:39] neg_lo:[0,1] neg_hi:[0,1]
	v_lshl_add_u64 v[16:17], v[16:17], 0, s[6:7]
	v_sub_f32_e32 v27, v28, v30
	v_pk_add_f32 v[22:23], v[22:23], v[30:31] neg_lo:[0,1] neg_hi:[0,1]
	v_sub_f32_e32 v27, v38, v27
	v_add_f32_e32 v22, v22, v27
	v_add_f32_e32 v22, v22, v23
	v_add_f32_e32 v22, v26, v22
	v_cndmask_b32_e32 v22, v235, v22, vcc
	v_cmp_neq_f32_e32 vcc, 1.0, v24
	v_lshl_add_u64 v[16:17], v[16:17], 0, v[0:1]
	global_load_dwordx4 v[26:29], v[16:17], off offset:512
	v_cndmask_b32_e32 v22, v236, v22, vcc
	v_cndmask_b32_e64 v22, v22, -v24, s[0:1]
	v_mul_f32_e32 v86, 0x3fb8aa3b, v22
	v_mul_f32_e32 v22, 0x43000000, v86
	v_cmp_gt_f32_e32 vcc, s39, v22
	s_and_b64 s[0:1], vcc, exec
	s_cselect_b32 s38, 0xffffffc0, 0
	s_lshl_b32 s0, s37, 2
	s_or_b32 s30, s0, s3
	s_mul_i32 s30, s30, 18
	s_or_b32 s0, s30, s2
	s_ashr_i32 s1, s0, 31
	s_lshl_b64 s[12:13], s[0:1], 7
	s_xor_b32 s0, s0, 1
	s_ashr_i32 s1, s0, 31
	s_lshl_b64 s[10:11], s[0:1], 7
	s_cmp_eq_u32 s2, 0
	v_cndmask_b32_e32 v87, 0, v234, vcc
	s_cselect_b64 vcc, -1, 0
	v_cndmask_b32_e32 v22, v25, v42, vcc
	v_cvt_f32_i32_e32 v22, v22
	v_cndmask_b32_e32 v23, v44, v43, vcc
	v_cvt_f32_i32_e32 v23, v23
	v_mul_f32_e32 v24, v86, v22
	v_cmp_gt_f32_e64 s[0:1], s39, v24
	v_mul_f32_e32 v30, v86, v23
	v_cmp_gt_f32_e64 s[2:3], s39, v30
	v_cndmask_b32_e64 v16, 0, v234, s[0:1]
	v_fmac_f32_e32 v16, v86, v22
	v_cndmask_b32_e64 v17, 0, v234, s[2:3]
	v_exp_f32_e32 v16, v16
	v_fmac_f32_e32 v17, v86, v23
	v_exp_f32_e32 v17, v17
	v_cndmask_b32_e64 v22, 0, v237, s[0:1]
	v_ldexp_f32 v55, v16, v22
	v_cndmask_b32_e64 v16, 0, v237, s[2:3]
	v_ldexp_f32 v56, v17, v16
	s_waitcnt vmcnt(3)
; DEVI unsigned cvt_pk_bf16(float lo, float hi) { unsigned r; asm volatile("v_cvt_pk_bf16_f32 %0, %1, %2" : "=v"(r) : "v"(lo), "v"(hi)); return r; }
; DEVI void ph_ret_state(const int wv, const Params& p, int l, unsigned char* lds_raw) {
;     ...
;         RS_LOAD(0);
;         __syncthreads();
;         RS_WRITE(0);
;         RS_LOAD(1);
;         int buf = 0;
;         for (int n = 0; n < 18; ++n) {
;             const int cid = dir == 0 ? n : (n < 2 ? 1 - n : 19 - n);
; #pragma unroll
;             for (int tt = 0; tt < 2; ++tt) { const int t = wave * 2 + tt, dkt = t >> 2, dvt = t & 3;
;                 u32x2 w; w.x = cvt_pk_bf16(R[tt][0], R[tt][1]); w.y = cvt_pk_bf16(R[tt][2], R[tt][3]);
;                 *(u32x2*)(RS + ((size_t)((b * 4 + h) * 18 + cid) * 128 + half * 64 + dvt * 16 + fr) * 128 + dir * 64 + dkt * 16 + 4 * fq) = w; }
;             if (n == 17) break;
;             __syncthreads();
;             if (n + 1 < 17) { RS_WRITE(buf ^ 1); if (n + 2 < 17) RS_LOAD(n + 2); }
	v_lshlrev_b32_e32 v16, 16, v10
	v_and_b32_e32 v10, 0xffff0000, v10
	v_mul_f32_e32 v16, v55, v16
	v_mul_f32_e32 v10, v55, v10
	s_barrier
	v_cvt_pk_bf16_f32 v10, v16, v10
	v_lshlrev_b32_e32 v16, 16, v11
	v_and_b32_e32 v11, 0xffff0000, v11
	v_mul_f32_e32 v16, v55, v16
	v_mul_f32_e32 v11, v55, v11
	v_cvt_pk_bf16_f32 v11, v16, v11
	v_lshlrev_b32_e32 v16, 16, v12
	v_and_b32_e32 v12, 0xffff0000, v12
	v_mul_f32_e32 v16, v55, v16
	v_mul_f32_e32 v12, v55, v12
	v_cvt_pk_bf16_f32 v12, v16, v12
	v_lshlrev_b32_e32 v16, 16, v13
	v_and_b32_e32 v13, 0xffff0000, v13
	v_mul_f32_e32 v13, v55, v13
	v_mul_f32_e32 v16, v55, v16
	v_cvt_pk_bf16_f32 v13, v16, v13
	ds_write_b128 v51, v[10:13]
	s_waitcnt vmcnt(2)
	ds_write_b128 v51, v[6:9] offset:18432
	s_waitcnt vmcnt(1)
	v_lshlrev_b32_e32 v6, 16, v2
	v_and_b32_e32 v2, 0xffff0000, v2
	v_mul_f32_e32 v6, v56, v6
	v_mul_f32_e32 v2, v56, v2
	v_cvt_pk_bf16_f32 v2, v6, v2
	v_lshlrev_b32_e32 v6, 16, v3
	v_and_b32_e32 v3, 0xffff0000, v3
	v_mul_f32_e32 v6, v56, v6
	v_mul_f32_e32 v3, v56, v3
	v_cvt_pk_bf16_f32 v3, v6, v3
	v_lshlrev_b32_e32 v6, 16, v4
	v_and_b32_e32 v4, 0xffff0000, v4
	v_mul_f32_e32 v6, v56, v6
	v_mul_f32_e32 v4, v56, v4
	v_cvt_pk_bf16_f32 v4, v6, v4
	v_lshlrev_b32_e32 v6, 16, v5
	v_and_b32_e32 v5, 0xffff0000, v5
	v_add_u32_e32 v16, s9, v25
	v_mul_f32_e32 v6, v56, v6
	v_mul_f32_e32 v5, v56, v5
	v_mad_i64_i32 v[10:11], s[0:1], v16, s46, v[14:15]
	v_cvt_pk_bf16_f32 v5, v6, v5
	v_lshl_add_u64 v[6:7], v[10:11], 0, s[4:5]
	v_lshl_add_u64 v[6:7], v[6:7], 0, v[0:1]
	global_load_dwordx4 v[6:9], v[6:7], off
	v_add_u32_e32 v16, 64, v16
	v_mad_i64_i32 v[16:17], s[0:1], v16, s46, v[14:15]
	v_lshl_add_u64 v[10:11], v[10:11], 0, s[18:19]
	v_lshl_add_u64 v[22:23], v[16:17], 0, s[4:5]
	v_lshl_add_u64 v[10:11], v[10:11], 0, s[6:7]
	v_lshl_add_u64 v[22:23], v[22:23], 0, v[0:1]
	v_lshl_add_u64 v[10:11], v[10:11], 0, v[0:1]
	global_load_dwordx4 v[30:33], v[22:23], off
	v_lshl_add_u64 v[16:17], v[16:17], 0, s[18:19]
	global_load_dwordx4 v[10:13], v[10:11], off offset:512
	v_lshl_add_u64 v[16:17], v[16:17], 0, s[6:7]
	v_lshl_add_u64 v[16:17], v[16:17], 0, v[0:1]
	global_load_dwordx4 v[34:37], v[16:17], off offset:512
	v_or_b32_e32 v24, s36, v19
	ds_write_b128 v51, v[2:5] offset:9216
	s_waitcnt vmcnt(4)
	ds_write_b128 v51, v[26:29] offset:27648
	v_or_b32_e32 v26, s12, v24
	v_mov_b32_e32 v3, s13
	v_or_b32_e32 v2, s97, v26
	s_mov_b32 s9, s19
	v_lshlrev_b64 v[16:17], 8, v[2:3]
	v_or_b32_e32 v2, s43, v26
	v_lshl_add_u64 v[22:23], v[20:21], 0, s[8:9]
	v_lshlrev_b64 v[2:3], 8, v[2:3]
	v_cvt_pk_bf16_f32 v4, v1, v1
	v_cvt_pk_bf16_f32 v5, v1, v1
	v_lshl_add_u64 v[16:17], v[22:23], 0, v[16:17]
	v_lshl_add_u64 v[2:3], v[22:23], 0, v[2:3]
	global_store_dwordx2 v[16:17], v[4:5], off
	v_cvt_pk_bf16_f32 v4, v1, v1
	v_cvt_pk_bf16_f32 v5, v1, v1
	global_store_dwordx2 v[2:3], v[4:5], off
	s_waitcnt lgkmcnt(0)
	s_barrier
	s_and_b64 s[0:1], vcc, exec
	s_movk_i32 s0, 0x880
	s_cselect_b32 s0, 0x100, s0
	v_fmac_f32_e32 v87, 0x43000000, v86
	s_mov_b32 s8, 0
	s_waitcnt vmcnt(5)
	v_lshlrev_b32_e32 v2, 16, v6
	v_and_b32_e32 v3, 0xffff0000, v6
	v_mul_f32_e32 v2, v55, v2
	v_mul_f32_e32 v3, v55, v3
	v_cvt_pk_bf16_f32 v2, v2, v3
	v_lshlrev_b32_e32 v3, 16, v7
	v_and_b32_e32 v4, 0xffff0000, v7
	v_mul_f32_e32 v3, v55, v3
	v_mul_f32_e32 v4, v55, v4
	v_cvt_pk_bf16_f32 v3, v3, v4
	v_lshlrev_b32_e32 v4, 16, v8
	v_and_b32_e32 v5, 0xffff0000, v8
	v_mul_f32_e32 v4, v55, v4
	v_mul_f32_e32 v5, v55, v5
	v_cvt_pk_bf16_f32 v4, v4, v5
	v_lshlrev_b32_e32 v5, 16, v9
	v_mul_f32_e32 v5, v55, v5
	v_and_b32_e32 v6, 0xffff0000, v9
	v_mul_f32_e32 v6, v55, v6
	v_cvt_pk_bf16_f32 v5, v5, v6
	ds_write_b128 v51, v[2:5] offset:36864
	s_waitcnt vmcnt(3)
	ds_write_b128 v51, v[10:13] offset:55296
	v_lshlrev_b32_e32 v2, 16, v30
	v_and_b32_e32 v3, 0xffff0000, v30
	v_mul_f32_e32 v2, v56, v2
	v_mul_f32_e32 v3, v56, v3
	v_cvt_pk_bf16_f32 v2, v2, v3
	v_lshlrev_b32_e32 v3, 16, v31
	v_and_b32_e32 v4, 0xffff0000, v31
	v_mul_f32_e32 v3, v56, v3
	v_mul_f32_e32 v4, v56, v4
	v_cvt_pk_bf16_f32 v3, v3, v4
	v_lshlrev_b32_e32 v4, 16, v32
	v_and_b32_e32 v5, 0xffff0000, v32
	v_mul_f32_e32 v4, v56, v4
	v_mul_f32_e32 v5, v56, v5
	v_cvt_pk_bf16_f32 v4, v4, v5
	v_lshlrev_b32_e32 v5, 16, v33
	v_mul_f32_e32 v5, v56, v5
	v_and_b32_e32 v6, 0xffff0000, v33
	v_mul_f32_e32 v6, v56, v6
	v_cvt_pk_bf16_f32 v5, v5, v6
	v_add_u32_e32 v10, s0, v57
	ds_write_b128 v51, v[2:5] offset:46080
	s_waitcnt vmcnt(2)
	ds_write_b128 v51, v[34:37] offset:64512
	v_mad_i64_i32 v[2:3], s[0:1], v10, s46, v[14:15]
	v_lshl_add_u64 v[4:5], v[2:3], 0, s[4:5]
	v_lshl_add_u64 v[2:3], v[2:3], 0, s[18:19]
	v_lshl_add_u64 v[2:3], v[2:3], 0, s[6:7]
	v_lshl_add_u64 v[4:5], v[4:5], 0, v[0:1]
	v_lshl_add_u64 v[6:7], v[2:3], 0, v[0:1]
	global_load_dwordx4 v[2:5], v[4:5], off
	s_nop 0
	global_load_dwordx4 v[6:9], v[6:7], off offset:512
	v_add_u32_e32 v10, 64, v10
	v_mad_i64_i32 v[16:17], s[0:1], v10, s46, v[14:15]
	v_lshl_add_u64 v[10:11], v[16:17], 0, s[4:5]
	v_lshl_add_u64 v[10:11], v[10:11], 0, v[0:1]
	global_load_dwordx4 v[10:13], v[10:11], off
	ds_read_b64_tr_b16 v[26:27], v88 offset:18432
	ds_read_b64_tr_b16 v[30:31], v52
	ds_read_b64_tr_b16 v[32:33], v52 offset:576
	ds_read_b64_tr_b16 v[34:35], v52 offset:4608
	ds_read_b64_tr_b16 v[36:37], v52 offset:5184
	ds_read_b64_tr_b16 v[28:29], v88 offset:19008
	ds_read_b64_tr_b16 v[38:39], v88 offset:23040
	ds_read_b64_tr_b16 v[58:59], v88 offset:23072
	ds_read_b64_tr_b16 v[64:65], v88 offset:19040
	ds_read_b64_tr_b16 v[62:63], v88 offset:18464
	ds_read_b64_tr_b16 v[68:69], v88 offset:32864
	s_waitcnt lgkmcnt(5)
; #define LAS __attribute__((address_space(3)))
; DEVI unsigned cvt_pk_bf16(float lo, float hi) { unsigned r; asm volatile("v_cvt_pk_bf16_f32 %0, %1, %2" : "=v"(r) : "v"(lo), "v"(hi)); return r; }
; #define MFMA16(X, Y, ACC) __builtin_amdgcn_mfma_f32_16x16x32_bf16((X), (Y), (ACC), 0, 0, 0)
; DEVI void ph_ret_state(const int wv, const Params& p, int l, unsigned char* lds_raw) {
;     ...
;         for (int n = 0; n < 18; ++n) {
;             const int cid = dir == 0 ? n : (n < 2 ? 1 - n : 19 - n);
; #pragma unroll
;             for (int tt = 0; tt < 2; ++tt) { const int t = wave * 2 + tt, dkt = t >> 2, dvt = t & 3;
;                 u32x2 w; w.x = cvt_pk_bf16(R[tt][0], R[tt][1]); w.y = cvt_pk_bf16(R[tt][2], R[tt][3]);
;                 *(u32x2*)(RS + ((size_t)((b * 4 + h) * 18 + cid) * 128 + half * 64 + dvt * 16 + fr) * 128 + dir * 64 + dkt * 16 + 4 * fq) = w; }
;             if (n == 17) break;
;             __syncthreads();
;             if (n + 1 < 17) { RS_WRITE(buf ^ 1); if (n + 2 < 17) RS_LOAD(n + 2); }
;             LAS unsigned char* Kb = Kt + buf * 36864; LAS unsigned char* Vb = Kb + 18432;
; #pragma unroll
;             for (int tt = 0; tt < 2; ++tt) { const int t = wave * 2 + tt, dkt = t >> 2, dvt = t & 3;
;                 f32x4 u = (f32x4){0.f, 0.f, 0.f, 0.f};
; #pragma unroll
;                 for (int ks = 0; ks < 4; ++ks) { const bf16x8 xf = tr_frag(Kb, 144, ks * 32 + 8 * fq, ks * 32 + 8 * fq + 4, dkt * 16, fr), yf = tr_frag(Vb, 144, ks * 32 + 8 * fq, ks * 32 + 8 * fq + 4, dvt * 16, fr); u = MFMA16(xf, yf, u); }
;                 R[tt] = R[tt] * gC + u; }
	v_mfma_f32_16x16x32_bf16 v[26:29], v[30:33], v[26:29], 0
	ds_read_b64_tr_b16 v[40:41], v88 offset:23616
	ds_read_b64_tr_b16 v[70:71], v52 offset:9216
	ds_read_b64_tr_b16 v[72:73], v52 offset:9792
	ds_read_b64_tr_b16 v[74:75], v88 offset:27648
	ds_read_b64_tr_b16 v[78:79], v88 offset:27680
	ds_read_b64_tr_b16 v[60:61], v88 offset:23648
	v_lshl_add_u64 v[16:17], v[16:17], 0, s[18:19]
	v_lshl_add_u64 v[16:17], v[16:17], 0, s[6:7]
	s_waitcnt lgkmcnt(5)
	v_mfma_f32_16x16x32_bf16 v[26:29], v[34:37], v[38:41], v[26:29]
	ds_read_b64_tr_b16 v[76:77], v88 offset:28224
	ds_read_b64_tr_b16 v[38:39], v52 offset:13824
	ds_read_b64_tr_b16 v[40:41], v52 offset:14400
	ds_read_b64_tr_b16 v[82:83], v88 offset:32256
	ds_read_b64_tr_b16 v[66:67], v88 offset:32288
	ds_read_b64_tr_b16 v[80:81], v88 offset:28256
	ds_read_b64_tr_b16 v[84:85], v88 offset:32832
	v_lshl_add_u64 v[16:17], v[16:17], 0, v[0:1]
	s_waitcnt lgkmcnt(6)
	v_mfma_f32_16x16x32_bf16 v[26:29], v[70:73], v[74:77], v[26:29]
	s_movk_i32 s0, 0x800
	s_cselect_b32 s0, 0x180, s0
	s_lshl_b32 s2, s36, 1
	s_waitcnt lgkmcnt(0)
	v_mfma_f32_16x16x32_bf16 v[74:77], v[38:41], v[82:85], v[26:29]
	v_mfma_f32_16x16x32_bf16 v[26:29], v[30:33], v[62:65], 0
	global_load_dwordx4 v[62:65], v[16:17], off offset:512
	v_exp_f32_e32 v16, v87
	v_mov_b32_e32 v17, s11
	v_mfma_f32_16x16x32_bf16 v[26:29], v[34:37], v[58:61], v[26:29]
	v_mfma_f32_16x16x32_bf16 v[34:37], v[70:73], v[78:81], v[26:29]
	v_mfma_f32_16x16x32_bf16 v[34:37], v[38:41], v[66:69], v[34:37]
	s_nop 5
	v_ldexp_f32 v26, v16, s38
	v_pk_fma_f32 v[30:31], v[26:27], 0, v[76:77] op_sel_hi:[0,0,1]
	v_pk_fma_f32 v[32:33], v[26:27], 0, v[74:75] op_sel_hi:[0,0,1]
	v_cvt_pk_bf16_f32 v28, v32, v33
	v_cvt_pk_bf16_f32 v29, v30, v31
	v_pk_fma_f32 v[38:39], v[26:27], 0, v[36:37] op_sel_hi:[0,0,1]
	v_pk_fma_f32 v[40:41], v[26:27], 0, v[34:35] op_sel_hi:[0,0,1]
	v_or_b32_e32 v27, s10, v24
	v_or_b32_e32 v16, s97, v27
	v_lshlrev_b64 v[34:35], 8, v[16:17]
	v_or_b32_e32 v16, s43, v27
	v_lshlrev_b64 v[16:17], 8, v[16:17]
	v_lshl_add_u64 v[34:35], v[22:23], 0, v[34:35]
	v_lshl_add_u64 v[16:17], v[22:23], 0, v[16:17]
	global_store_dwordx2 v[34:35], v[28:29], off
	v_cvt_pk_bf16_f32 v28, v40, v41
	v_cvt_pk_bf16_f32 v29, v38, v39
	global_store_dwordx2 v[16:17], v[28:29], off
	s_barrier
	s_waitcnt vmcnt(5)
	v_lshlrev_b32_e32 v16, 16, v2
	v_and_b32_e32 v2, 0xffff0000, v2
	v_mul_f32_e32 v16, v55, v16
	v_mul_f32_e32 v2, v55, v2
	v_cvt_pk_bf16_f32 v2, v16, v2
	v_lshlrev_b32_e32 v16, 16, v3
	v_and_b32_e32 v3, 0xffff0000, v3
	v_mul_f32_e32 v16, v55, v16
	v_mul_f32_e32 v3, v55, v3
	v_cvt_pk_bf16_f32 v3, v16, v3
	v_lshlrev_b32_e32 v16, 16, v4
	v_and_b32_e32 v4, 0xffff0000, v4
	v_mul_f32_e32 v16, v55, v16
	v_mul_f32_e32 v4, v55, v4
	v_cvt_pk_bf16_f32 v4, v16, v4
	v_lshlrev_b32_e32 v16, 16, v5
	v_and_b32_e32 v5, 0xffff0000, v5
	v_mul_f32_e32 v5, v55, v5
	v_mul_f32_e32 v16, v55, v16
	v_cvt_pk_bf16_f32 v5, v16, v5
	ds_write_b128 v51, v[2:5]
	s_waitcnt vmcnt(4)
	ds_write_b128 v51, v[6:9] offset:18432
	s_waitcnt vmcnt(3)
	v_lshlrev_b32_e32 v2, 16, v10
	v_and_b32_e32 v3, 0xffff0000, v10
	v_mul_f32_e32 v2, v56, v2
	v_mul_f32_e32 v3, v56, v3
	v_cvt_pk_bf16_f32 v2, v2, v3
	v_lshlrev_b32_e32 v3, 16, v11
	v_and_b32_e32 v4, 0xffff0000, v11
	v_mul_f32_e32 v3, v56, v3
	v_mul_f32_e32 v4, v56, v4
	v_cvt_pk_bf16_f32 v3, v3, v4
	v_lshlrev_b32_e32 v4, 16, v12
	v_and_b32_e32 v5, 0xffff0000, v12
	v_mul_f32_e32 v4, v56, v4
	v_mul_f32_e32 v5, v56, v5
	v_cvt_pk_bf16_f32 v4, v4, v5
	v_lshlrev_b32_e32 v5, 16, v13
	v_mul_f32_e32 v5, v56, v5
	v_and_b32_e32 v6, 0xffff0000, v13
	v_mul_f32_e32 v6, v56, v6
	v_cvt_pk_bf16_f32 v5, v5, v6
	v_add_u32_e32 v10, s0, v57
	ds_write_b128 v51, v[2:5] offset:9216
	s_waitcnt vmcnt(2)
	ds_write_b128 v51, v[62:65] offset:27648
	v_mad_i64_i32 v[2:3], s[0:1], v10, s46, v[14:15]
	v_lshl_add_u64 v[4:5], v[2:3], 0, s[4:5]
	v_lshl_add_u64 v[2:3], v[2:3], 0, s[18:19]
	v_lshl_add_u64 v[2:3], v[2:3], 0, s[6:7]
	v_lshl_add_u64 v[4:5], v[4:5], 0, v[0:1]
	v_lshl_add_u64 v[6:7], v[2:3], 0, v[0:1]
	v_add_u32_e32 v10, 64, v10
	global_load_dwordx4 v[2:5], v[4:5], off
	s_nop 0
	global_load_dwordx4 v[6:9], v[6:7], off offset:512
	v_mad_i64_i32 v[28:29], s[0:1], v10, s46, v[14:15]
	ds_read_b64_tr_b16 v[10:11], v52 offset:36864
	ds_read_b64_tr_b16 v[12:13], v52 offset:37440
	ds_read_b64_tr_b16 v[34:35], v52 offset:41472
	ds_read_b64_tr_b16 v[36:37], v52 offset:42048
	ds_read_b64_tr_b16 v[16:17], v88 offset:55872
	ds_read_b64_tr_b16 v[14:15], v88 offset:55296
	ds_read_b64_tr_b16 v[60:61], v88 offset:55904
	ds_read_b64_tr_b16 v[58:59], v88 offset:55328
	ds_read_b64_tr_b16 v[62:63], v88 offset:59904
	ds_read_b64_tr_b16 v[64:65], v88 offset:60480
	s_waitcnt lgkmcnt(4)
	v_mfma_f32_16x16x32_bf16 v[14:17], v[10:13], v[14:17], 0
	ds_read_b64_tr_b16 v[68:69], v88 offset:60512
	ds_read_b64_tr_b16 v[66:67], v88 offset:59936
	v_lshl_add_u64 v[86:87], v[28:29], 0, s[4:5]
	v_lshl_add_u64 v[86:87], v[86:87], 0, v[0:1]
	s_waitcnt lgkmcnt(2)
	v_mfma_f32_16x16x32_bf16 v[14:17], v[34:37], v[62:65], v[14:17]
	ds_read_b64_tr_b16 v[62:63], v52 offset:46080
	ds_read_b64_tr_b16 v[64:65], v52 offset:46656
	ds_read_b64_tr_b16 v[70:71], v88 offset:64512
	ds_read_b64_tr_b16 v[72:73], v88 offset:65088
	ds_read_b64_tr_b16 v[74:75], v52 offset:50688
	ds_read_b64_tr_b16 v[76:77], v52 offset:51264
	ds_read_b64_tr_b16 v[80:81], v54 offset:55296
	ds_read_b64_tr_b16 v[78:79], v53 offset:55296
	ds_read_b64_tr_b16 v[84:85], v88 offset:65120
	ds_read_b64_tr_b16 v[82:83], v88 offset:64544
	s_mov_b32 s5, 4
	s_lshl_b32 s0, s4, 1
	s_waitcnt lgkmcnt(6)
	v_mfma_f32_16x16x32_bf16 v[14:17], v[62:65], v[70:73], v[14:17]
	ds_read_b64_tr_b16 v[72:73], v54 offset:55328
	ds_read_b64_tr_b16 v[70:71], v53 offset:55328
	s_waitcnt lgkmcnt(4)
	v_mfma_f32_16x16x32_bf16 v[78:81], v[74:77], v[78:81], v[14:17]
	s_nop 3
	v_lshl_add_u64 v[14:15], v[28:29], 0, s[18:19]
	v_lshl_add_u64 v[14:15], v[14:15], 0, s[6:7]
	v_lshl_add_u64 v[14:15], v[14:15], 0, v[0:1]
	v_mfma_f32_16x16x32_bf16 v[58:61], v[10:13], v[58:61], 0
	global_load_dwordx4 v[10:13], v[86:87], off
	s_nop 0
	global_load_dwordx4 v[14:17], v[14:15], off offset:512
	global_load_dword v140, v1, s[24:25]
	global_load_dword v141, v1, s[24:25]
	v_mov_b32_e32 v28, v26
	v_mov_b32_e32 v29, v26
	v_mfma_f32_16x16x32_bf16 v[34:37], v[34:37], v[66:69], v[58:61]
	s_mov_b32 s6, 17
	s_lshl_b32 s18, s31, 1
	s_waitcnt lgkmcnt(2)
	v_mfma_f32_16x16x32_bf16 v[58:61], v[62:65], v[82:85], v[34:37]
	s_nop 3
	v_fma_f32 v36, v26, v30, v80
	v_fma_f32 v37, v26, v31, v81
	v_pk_fma_f32 v[34:35], v[26:27], v[32:33], v[78:79] op_sel_hi:[0,1,1]
	s_waitcnt lgkmcnt(0)
	v_mfma_f32_16x16x32_bf16 v[30:33], v[74:77], v[70:73], v[58:61]
	s_nop 7
	v_pk_fma_f32 v[32:33], v[26:27], v[38:39], v[32:33] op_sel_hi:[0,1,1]
	v_pk_fma_f32 v[30:31], v[26:27], v[40:41], v[30:31] op_sel_hi:[0,1,1]
; #define LAS __attribute__((address_space(3)))
; DEVI unsigned cvt_pk_bf16(float lo, float hi) { unsigned r; asm volatile("v_cvt_pk_bf16_f32 %0, %1, %2" : "=v"(r) : "v"(lo), "v"(hi)); return r; }
; #define MFMA16(X, Y, ACC) __builtin_amdgcn_mfma_f32_16x16x32_bf16((X), (Y), (ACC), 0, 0, 0)
; DEVI void ph_ret_state(const int wv, const Params& p, int l, unsigned char* lds_raw) {
;     ...
;         for (int n = 0; n < 18; ++n) {
;             const int cid = dir == 0 ? n : (n < 2 ? 1 - n : 19 - n);
; #pragma unroll
;             for (int tt = 0; tt < 2; ++tt) { const int t = wave * 2 + tt, dkt = t >> 2, dvt = t & 3;
;                 u32x2 w; w.x = cvt_pk_bf16(R[tt][0], R[tt][1]); w.y = cvt_pk_bf16(R[tt][2], R[tt][3]);
;                 *(u32x2*)(RS + ((size_t)((b * 4 + h) * 18 + cid) * 128 + half * 64 + dvt * 16 + fr) * 128 + dir * 64 + dkt * 16 + 4 * fq) = w; }
;             if (n == 17) break;
;             __syncthreads();
;             if (n + 1 < 17) { RS_WRITE(buf ^ 1); if (n + 2 < 17) RS_LOAD(n + 2); }
;             LAS unsigned char* Kb = Kt + buf * 36864; LAS unsigned char* Vb = Kb + 18432;
; #pragma unroll
;             for (int tt = 0; tt < 2; ++tt) { const int t = wave * 2 + tt, dkt = t >> 2, dvt = t & 3;
;                 f32x4 u = (f32x4){0.f, 0.f, 0.f, 0.f};
; #pragma unroll
;                 for (int ks = 0; ks < 4; ++ks) { const bf16x8 xf = tr_frag(Kb, 144, ks * 32 + 8 * fq, ks * 32 + 8 * fq + 4, dkt * 16, fr), yf = tr_frag(Vb, 144, ks * 32 + 8 * fq, ks * 32 + 8 * fq + 4, dvt * 16, fr); u = MFMA16(xf, yf, u); }
;                 R[tt] = R[tt] * gC + u; }
;             buf ^= 1;
;         }
.LBB0_543:
	s_add_i32 s1, s5, -2
	s_waitcnt vmcnt(5)
	v_lshlrev_b32_e32 v27, 16, v2
	v_and_b32_e32 v38, 0xffff0000, v2
	v_mul_f32_e32 v27, v55, v27
	v_mul_f32_e32 v38, v55, v38
	s_barrier
	v_cvt_pk_bf16_f32 v38, v27, v38
	v_lshlrev_b32_e32 v27, 16, v3
	v_and_b32_e32 v39, 0xffff0000, v3
	v_mul_f32_e32 v27, v55, v27
	v_mul_f32_e32 v39, v55, v39
	v_cvt_pk_bf16_f32 v39, v27, v39
	v_lshlrev_b32_e32 v27, 16, v4
	v_and_b32_e32 v40, 0xffff0000, v4
	s_xor_b32 s7, s8, 1
	v_mul_f32_e32 v27, v55, v27
	v_mul_f32_e32 v40, v55, v40
	s_mul_i32 s3, s7, 0x9000
	v_cvt_pk_bf16_f32 v40, v27, v40
	v_lshlrev_b32_e32 v27, 16, v5
	v_and_b32_e32 v41, 0xffff0000, v5
	s_add_i32 s4, s3, 0
	v_mul_f32_e32 v27, v55, v27
	v_mul_f32_e32 v41, v55, v41
	v_cvt_pk_bf16_f32 v41, v27, v41
	v_add3_u32 v27, s4, v45, v48
	ds_write_b128 v27, v[38:41]
	s_waitcnt vmcnt(4)
	ds_write_b128 v27, v[6:9] offset:18432
	s_waitcnt vmcnt(3)
	v_lshlrev_b32_e32 v38, 16, v10
	v_and_b32_e32 v39, 0xffff0000, v10
	v_mul_f32_e32 v38, v56, v38
	v_mul_f32_e32 v39, v56, v39
	v_cvt_pk_bf16_f32 v38, v38, v39
	v_lshlrev_b32_e32 v39, 16, v11
	v_and_b32_e32 v40, 0xffff0000, v11
	v_mul_f32_e32 v39, v56, v39
	v_mul_f32_e32 v40, v56, v40
	v_cvt_pk_bf16_f32 v39, v39, v40
	v_lshlrev_b32_e32 v40, 16, v12
	v_and_b32_e32 v41, 0xffff0000, v12
	v_mul_f32_e32 v40, v56, v40
	v_mul_f32_e32 v41, v56, v41
	v_cvt_pk_bf16_f32 v40, v40, v41
	v_lshlrev_b32_e32 v41, 16, v13
	v_mul_f32_e32 v41, v56, v41
	v_and_b32_e32 v58, 0xffff0000, v13
	s_cmp_gt_u32 s1, 14
	v_mul_f32_e32 v58, v56, v58
	v_cvt_pk_bf16_f32 v41, v41, v58
	ds_write_b128 v27, v[38:41] offset:9216
	s_waitcnt vmcnt(2)
	ds_write_b128 v27, v[14:17] offset:27648
	s_cbranch_scc1 .LBB0_545
	s_add_i32 s1, s6, -2
	s_and_b64 s[10:11], vcc, exec
	s_cselect_b32 s1, s5, s1
	v_lshl_add_u32 v12, s1, 7, v57
	v_mov_b64_e32 v[10:11], s[24:25]
	v_mad_i64_i32 v[2:3], s[10:11], v12, s46, v[10:11]
	v_add_u32_e32 v12, 64, v12
	s_mov_b32 s1, s19
	v_mad_i64_i32 v[10:11], s[10:11], v12, s46, v[10:11]
	v_lshl_add_u64 v[4:5], v[2:3], 0, s[18:19]
	v_lshl_add_u64 v[2:3], v[2:3], 0, s[0:1]
	s_mov_b32 s3, s19
	v_lshl_add_u64 v[12:13], v[10:11], 0, s[18:19]
	v_lshl_add_u64 v[10:11], v[10:11], 0, s[0:1]
	v_lshl_add_u64 v[2:3], v[2:3], 0, s[2:3]
	v_lshl_add_u64 v[10:11], v[10:11], 0, s[2:3]
	v_lshl_add_u64 v[4:5], v[4:5], 0, v[0:1]
	v_lshl_add_u64 v[6:7], v[2:3], 0, v[0:1]
	v_lshl_add_u64 v[12:13], v[12:13], 0, v[0:1]
	v_lshl_add_u64 v[14:15], v[10:11], 0, v[0:1]
	global_load_dwordx4 v[2:5], v[4:5], off
	s_nop 0
	global_load_dwordx4 v[6:9], v[6:7], off offset:512
	s_nop 0
	global_load_dwordx4 v[10:13], v[12:13], off
	s_nop 0
	global_load_dwordx4 v[14:17], v[14:15], off offset:512
.LBB0_545:
	s_add_i32 s1, s5, -2
	s_and_b64 s[10:11], vcc, exec
	s_cselect_b32 s3, s1, s6
	s_add_i32 s10, s3, s30
	s_ashr_i32 s11, s10, 31
	s_lshl_b64 s[10:11], s[10:11], 7
	v_or_b32_e32 v27, s10, v24
	v_mov_b32_e32 v41, s11
	v_or_b32_e32 v40, s97, v27
	v_lshlrev_b64 v[58:59], 8, v[40:41]
	v_or_b32_e32 v40, s43, v27
	v_cvt_pk_bf16_f32 v38, v34, v35
	v_lshl_add_u64 v[58:59], v[22:23], 0, v[58:59]
	v_lshlrev_b64 v[40:41], 8, v[40:41]
	v_cvt_pk_bf16_f32 v39, v36, v37
	global_store_dwordx2 v[58:59], v[38:39], off
	v_cvt_pk_bf16_f32 v38, v30, v31
	v_lshl_add_u64 v[40:41], v[22:23], 0, v[40:41]
	v_cvt_pk_bf16_f32 v39, v32, v33
	global_store_dwordx2 v[40:41], v[38:39], off
	s_mul_i32 s1, s8, 0x9000
	s_add_i32 s1, s1, 0
	s_add_i32 s3, s1, s96
	v_add3_u32 v27, s3, v47, v49
	s_add_i32 s1, s42, s1
	ds_read_b64_tr_b16 v[38:39], v27
	ds_read_b64_tr_b16 v[40:41], v27 offset:576
	v_add3_u32 v82, s1, v47, v49
	ds_read_b64_tr_b16 v[60:61], v82 offset:19008
	ds_read_b64_tr_b16 v[58:59], v82 offset:18432
	ds_read_b64_tr_b16 v[62:63], v82 offset:18464
	ds_read_b64_tr_b16 v[66:67], v27 offset:4608
	ds_read_b64_tr_b16 v[68:69], v27 offset:5184
	ds_read_b64_tr_b16 v[70:71], v82 offset:23040
	ds_read_b64_tr_b16 v[72:73], v82 offset:23616
	s_waitcnt lgkmcnt(5)
	v_mfma_f32_16x16x32_bf16 v[58:61], v[38:41], v[58:61], 0
	s_add_i32 s5, s5, 1
	s_add_i32 s6, s6, -1
	s_cmp_lg_u32 s6, 3
	s_waitcnt lgkmcnt(0)
	v_mfma_f32_16x16x32_bf16 v[58:61], v[66:69], v[70:73], v[58:61]
	ds_read_b64_tr_b16 v[70:71], v27 offset:9216
	ds_read_b64_tr_b16 v[72:73], v27 offset:9792
	ds_read_b64_tr_b16 v[74:75], v82 offset:27648
	ds_read_b64_tr_b16 v[76:77], v82 offset:28224
	s_waitcnt lgkmcnt(0)
	v_mfma_f32_16x16x32_bf16 v[58:61], v[70:73], v[74:77], v[58:61]
	ds_read_b64_tr_b16 v[74:75], v27 offset:13824
	ds_read_b64_tr_b16 v[76:77], v27 offset:14400
	ds_read_b64_tr_b16 v[78:79], v82 offset:32256
	ds_read_b64_tr_b16 v[80:81], v82 offset:32832
	ds_read_b64_tr_b16 v[64:65], v82 offset:19040
	v_mov_b32_e32 v27, v26
	s_waitcnt lgkmcnt(1)
	v_mfma_f32_16x16x32_bf16 v[58:61], v[74:77], v[78:81], v[58:61]
	s_waitcnt lgkmcnt(0)
	v_mfma_f32_16x16x32_bf16 v[38:41], v[38:41], v[62:65], 0
	s_nop 5
	v_fma_f32 v36, v26, v36, v60
	v_fma_f32 v37, v27, v37, v61
	v_pk_fma_f32 v[34:35], v[28:29], v[34:35], v[58:59]
	ds_read_b64_tr_b16 v[58:59], v82 offset:23072
	ds_read_b64_tr_b16 v[60:61], v82 offset:23648
	s_waitcnt lgkmcnt(0)
	v_mfma_f32_16x16x32_bf16 v[38:41], v[66:69], v[58:61], v[38:41]
	ds_read_b64_tr_b16 v[58:59], v82 offset:27680
	ds_read_b64_tr_b16 v[60:61], v82 offset:28256
	s_waitcnt lgkmcnt(0)
	v_mfma_f32_16x16x32_bf16 v[38:41], v[70:73], v[58:61], v[38:41]
	ds_read_b64_tr_b16 v[58:59], v82 offset:32288
	ds_read_b64_tr_b16 v[60:61], v82 offset:32864
	s_waitcnt lgkmcnt(0)
	v_mfma_f32_16x16x32_bf16 v[38:41], v[74:77], v[58:61], v[38:41]
	s_nop 7
	v_pk_fma_f32 v[32:33], v[26:27], v[32:33], v[40:41]
	v_pk_fma_f32 v[30:31], v[28:29], v[30:31], v[38:39]
	s_cbranch_scc0 .LBB0_541
	s_mov_b32 s8, s7
	s_branch .LBB0_543
